# adds: attention PV quarters issue V-fragment reads right after the barrier, counted LDS waits before first PV MFMAs
# baseline (speedup 1.0000x reference)
.LBB0_596:
	v_or_b32_e32 v14, s61, v210
	v_add_u32_e32 v223, v209, v14
	v_exp_f32_e32 v17, v150
	v_exp_f32_e32 v212, v151
	v_exp_f32_e32 v213, v152
	v_exp_f32_e32 v214, v153
	s_waitcnt lgkmcnt(0)
	s_barrier
	v_xad_u32 v248, v14, 32, v209
	ds_read_b128 v[150:153], v223 offset:32768
	ds_read_b128 v[224:227], v223 offset:36864
	ds_read_b128 v[228:231], v248 offset:36864
	ds_read_b128 v[232:235], v223 offset:40960
	ds_read_b128 v[236:239], v248 offset:40960
	ds_read_b128 v[240:243], v223 offset:45056
	ds_read_b128 v[244:247], v248 offset:45056
	v_exp_f32_e32 v2, v146
	v_exp_f32_e32 v4, v147
	v_exp_f32_e32 v15, v148
	v_exp_f32_e32 v16, v149
	v_exp_f32_e32 v215, v154
	v_exp_f32_e32 v216, v155
	v_exp_f32_e32 v217, v156
	v_exp_f32_e32 v218, v157
	ds_read_b128 v[154:157], v248 offset:32768
	v_cvt_pk_bf16_f32 v146, v2, v4
	v_cvt_pk_bf16_f32 v148, v17, v212
	v_cvt_pk_bf16_f32 v147, v15, v16
	v_cvt_pk_bf16_f32 v149, v213, v214
	s_waitcnt lgkmcnt(7)
	v_mfma_f32_32x32x16_bf16 v[130:145], v[150:153], v[146:149], v[130:145]
	v_exp_f32_e32 v219, v158
	v_exp_f32_e32 v220, v159
	v_exp_f32_e32 v221, v160
	v_exp_f32_e32 v222, v161
	v_cvt_pk_bf16_f32 v150, v215, v216
	v_cvt_pk_bf16_f32 v151, v217, v218
	v_cvt_pk_bf16_f32 v152, v219, v220
	v_cvt_pk_bf16_f32 v153, v221, v222
	ds_read_b128 v[158:161], v223 offset:49152
	s_lshl_b64 s[48:49], s[4:5], 7
	s_waitcnt lgkmcnt(1)
	v_mfma_f32_32x32x16_bf16 v[130:145], v[154:157], v[150:153], v[130:145]
	ds_read_b128 v[154:157], v248 offset:49152
	s_add_i32 m0, s43, 0x8000
	s_and_b64 vcc, exec, s[0:1]
	v_mfma_f32_32x32x16_bf16 v[114:129], v[224:227], v[146:149], v[114:129]
	ds_read_b128 v[224:227], v223 offset:53248
	v_mfma_f32_32x32x16_bf16 v[114:129], v[228:231], v[150:153], v[114:129]
	ds_read_b128 v[228:231], v248 offset:53248
	v_mfma_f32_32x32x16_bf16 v[98:113], v[232:235], v[146:149], v[98:113]
	ds_read_b128 v[232:235], v223 offset:57344
	v_mfma_f32_32x32x16_bf16 v[98:113], v[236:239], v[150:153], v[98:113]
	ds_read_b128 v[236:239], v248 offset:57344
	v_mfma_f32_32x32x16_bf16 v[82:97], v[240:243], v[146:149], v[82:97]
	ds_read_b128 v[240:243], v223 offset:61440
	v_mfma_f32_32x32x16_bf16 v[82:97], v[244:247], v[150:153], v[82:97]
	ds_read_b128 v[244:247], v248 offset:61440
	s_waitcnt lgkmcnt(0)
	v_mfma_f32_32x32x16_bf16 v[66:81], v[158:161], v[146:149], v[66:81]
	v_mfma_f32_32x32x16_bf16 v[66:81], v[154:157], v[150:153], v[66:81]
	v_lshl_add_u64 v[154:155], v[192:193], 0, s[48:49]
	global_load_lds_dwordx4 v[154:155], off
	v_lshl_add_u64 v[154:155], v[154:155], 0, s[38:39]
	s_add_i32 m0, s43, 0xa000
	s_nop 0
	global_load_lds_dwordx4 v[154:155], off
	v_lshl_add_u64 v[154:155], v[154:155], 0, s[38:39]
	s_add_i32 m0, s43, 0xc000
	v_mfma_f32_32x32x16_bf16 v[50:65], v[224:227], v[146:149], v[50:65]
	global_load_lds_dwordx4 v[154:155], off
	s_add_i32 m0, s43, 0xe000
	v_mfma_f32_32x32x16_bf16 v[34:49], v[232:235], v[146:149], v[34:49]
	v_mfma_f32_32x32x16_bf16 v[18:33], v[240:243], v[146:149], v[18:33]
	v_lshl_add_u64 v[146:147], v[154:155], 0, s[38:39]
	global_load_lds_dwordx4 v[146:147], off
	s_waitcnt lgkmcnt(0)
	s_barrier
	v_mfma_f32_32x32x16_bf16 v[50:65], v[228:231], v[150:153], v[50:65]
	v_mfma_f32_32x32x16_bf16 v[34:49], v[236:239], v[150:153], v[34:49]
	v_mfma_f32_32x32x16_bf16 v[18:33], v[244:247], v[150:153], v[18:33]
	s_cbranch_vccnz .LBB0_598
	s_setprio 1

.LBB0_602:
	s_waitcnt vmcnt(4)
	v_xad_u32 v236, v14, 64, v209
	v_exp_f32_e32 v2, v146
	v_exp_f32_e32 v4, v147
	v_exp_f32_e32 v7, v148
	v_exp_f32_e32 v16, v149
	s_waitcnt lgkmcnt(0)
	s_barrier
	v_xad_u32 v237, v14, s83, v209
	ds_read_b128 v[146:149], v236 offset:32768
	ds_read_b128 v[212:215], v236 offset:40960
	ds_read_b128 v[216:219], v237 offset:40960
	ds_read_b128 v[220:223], v236 offset:45056
	ds_read_b128 v[224:227], v237 offset:45056
	ds_read_b128 v[12:15], v237 offset:32768
	v_exp_f32_e32 v17, v150
	v_exp_f32_e32 v211, v151
	v_exp_f32_e32 v228, v152
	v_exp_f32_e32 v229, v153
	ds_read_b128 v[150:153], v236 offset:36864
	v_exp_f32_e32 v230, v154
	v_exp_f32_e32 v231, v155
	v_exp_f32_e32 v232, v156
	v_exp_f32_e32 v233, v157
	ds_read_b128 v[154:157], v237 offset:36864
	v_cvt_pk_bf16_f32 v8, v2, v4
	v_cvt_pk_bf16_f32 v9, v7, v16
	v_cvt_pk_bf16_f32 v10, v17, v211
	v_cvt_pk_bf16_f32 v11, v228, v229
	s_waitcnt lgkmcnt(7)
	v_mfma_f32_32x32x16_bf16 v[130:145], v[146:149], v[8:11], v[130:145]
	v_exp_f32_e32 v234, v158
	v_exp_f32_e32 v235, v159
	v_exp_f32_e32 v238, v160
	v_exp_f32_e32 v239, v161
	v_cvt_pk_bf16_f32 v146, v230, v231
	v_cvt_pk_bf16_f32 v147, v232, v233
	v_cvt_pk_bf16_f32 v148, v234, v235
	v_cvt_pk_bf16_f32 v149, v238, v239
	ds_read_b128 v[158:161], v236 offset:49152
	v_add_f32_e32 v2, v2, v4
	s_waitcnt lgkmcnt(3)
	v_mfma_f32_32x32x16_bf16 v[130:145], v[12:15], v[146:149], v[130:145]
	ds_read_b128 v[12:15], v237 offset:49152
	v_add_f32_e32 v2, 0, v2
	v_add_f32_e32 v4, v16, v7
	v_add_f32_e32 v2, v4, v2
	v_add_f32_e32 v4, v211, v17
	v_add_f32_e32 v2, v4, v2
	v_add_f32_e32 v4, v229, v228
	s_waitcnt lgkmcnt(3)
	v_mfma_f32_32x32x16_bf16 v[114:129], v[150:153], v[8:11], v[114:129]
	ds_read_b128 v[150:153], v236 offset:53248
	v_add_f32_e32 v2, v4, v2
	v_add_f32_e32 v4, v231, v230
	v_add_f32_e32 v2, v4, v2
	v_add_f32_e32 v4, v233, v232
	v_add_f32_e32 v2, v4, v2
	v_add_f32_e32 v4, v235, v234
	s_waitcnt lgkmcnt(3)
	v_mfma_f32_32x32x16_bf16 v[114:129], v[154:157], v[146:149], v[114:129]
	ds_read_b128 v[154:157], v237 offset:53248
	v_add_f32_e32 v2, v4, v2
	v_add_f32_e32 v4, v238, v239
	v_add_f32_e32 v2, v4, v2
	s_add_i32 s60, s60, 0x10000
	v_add_f32_e32 v211, v6, v2
	s_cmp_eq_u32 s58, s42
	v_mfma_f32_32x32x16_bf16 v[98:113], v[212:215], v[8:11], v[98:113]
	ds_read_b128 v[212:215], v236 offset:57344
	v_mfma_f32_32x32x16_bf16 v[98:113], v[216:219], v[146:149], v[98:113]
	ds_read_b128 v[216:219], v237 offset:57344
	v_mfma_f32_32x32x16_bf16 v[82:97], v[220:223], v[8:11], v[82:97]
	ds_read_b128 v[220:223], v236 offset:61440
	v_mfma_f32_32x32x16_bf16 v[82:97], v[224:227], v[146:149], v[82:97]
	ds_read_b128 v[224:227], v237 offset:61440
	s_waitcnt vmcnt(0)
	s_waitcnt lgkmcnt(0)
	s_barrier
	s_waitcnt lgkmcnt(0)
	v_mfma_f32_32x32x16_bf16 v[66:81], v[158:161], v[8:11], v[66:81]
	v_mfma_f32_32x32x16_bf16 v[50:65], v[150:153], v[8:11], v[50:65]
	v_mfma_f32_32x32x16_bf16 v[34:49], v[212:215], v[8:11], v[34:49]
	v_mfma_f32_32x32x16_bf16 v[18:33], v[220:223], v[8:11], v[18:33]
	v_mfma_f32_32x32x16_bf16 v[66:81], v[12:15], v[146:149], v[66:81]
	v_mfma_f32_32x32x16_bf16 v[50:65], v[154:157], v[146:149], v[50:65]
	v_mfma_f32_32x32x16_bf16 v[34:49], v[216:219], v[146:149], v[34:49]
	v_mfma_f32_32x32x16_bf16 v[18:33], v[224:227], v[146:149], v[18:33]
	s_cbranch_scc0 .LBB0_584
	v_and_b32_e32 v2, 63, v186
	s_cmpk_lt_u32 s56, 0x100
	s_cbranch_scc0 .LBB0_605
